# GEMM3 last column tile (pn 20, upper 128 columns are zero padding never stored): skip the bj=1 MFMA runs; these 64 tiles are exactly the partial sixth round
# baseline (speedup 1.0000x reference)
; #define PG8_STAGE(bufoff, gbase, voff) do { _Pragma("unroll") for (int _i = 0; _i < 2; ++_i) \
;         __builtin_amdgcn_global_load_lds((const unsigned*)((const char*)(gbase) + (voff)[_i]), (LAS unsigned*)(lds + (bufoff) + ldsw + _i * 8192), 16, 0, 0); } while (0)
; #define PG8_LDA(dst, b, h) do { _Pragma("unroll") for (int m = 0; m < 4; ++m) _Pragma("unroll") for (int k = 0; k < 2; ++k) dst[m][k] = *(const LAS h16x8*)(lds + PG8_SA(b, h) + aoff + m * 2048 + k * 1024); } while (0)
; #define PG8_LDB(dst, b, h) do { _Pragma("unroll") for (int n = 0; n < 2; ++n) _Pragma("unroll") for (int k = 0; k < 2; ++k) dst[n][k] = *(const LAS h16x8*)(lds + PG8_SB(b, h) + boff + n * 2048 + k * 1024); } while (0)
; #define PG8_MMA(ai, bj, At, Bt) do { __builtin_amdgcn_s_setprio(1); _Pragma("unroll") for (int m = 0; m < 4; ++m) _Pragma("unroll") for (int n = 0; n < 2; ++n) _Pragma("unroll") for (int k = 0; k < 2; ++k) \
;         acc[ai][bj][m][n] = __builtin_amdgcn_mfma_f32_16x16x32_f16(Bt[n][k], At[m][k], acc[ai][bj][m][n], 0, 0, 0); __builtin_amdgcn_s_setprio(0); } while (0)
; #define PG8_WAIT_V(n) asm volatile("s_waitcnt vmcnt(" #n ")" ::: "memory")
; #define PG8_WAIT_L(n) asm volatile("s_waitcnt lgkmcnt(" #n ")" ::: "memory")
; #define PG8_BAR __builtin_amdgcn_s_barrier()
; #define PG8_SCHED __builtin_amdgcn_sched_barrier(0)
; template <class Epi>
; __device__ __forceinline__ void gemm_phase(LAS unsigned char* lds, const Gemm g, const StaticOrder& S, const Epi& E) {
;     ...
;             PG8_LDB(B0, 0, 0); PG8_SCHED; PG8_LDA(At, 0, 0); PG8_STAGE(PG8_SA(1, 1), a1 + hstep, voffA);
;             PG8_WAIT_L(8); PG8_BAR; PG8_WAIT_L(0); PG8_MMA(0, 0, At, B0); PG8_BAR; PG8_SCHED;
;             PG8_LDB(B1, 0, 1); PG8_STAGE(PG8_SB(0, 0), b2, voffB);
;             PG8_BAR; PG8_WAIT_L(0); PG8_MMA(0, 1, At, B1); PG8_BAR;
;             PG8_LDA(At, 0, 1); PG8_STAGE(PG8_SA(0, 0), a2, voffA);
;             PG8_BAR; PG8_WAIT_L(0); PG8_MMA(1, 0, At, B0); PG8_BAR; PG8_SCHED;
;             PG8_STAGE(PG8_SB(0, 1), b2 + hstep, voffB);
;             PG8_WAIT_V(6); PG8_BAR; PG8_MMA(1, 1, At, B1); PG8_BAR;
.LBB0_485:
	ds_read_b128 v[148:151], v165
	ds_read_b128 v[152:155], v165 offset:1024
	ds_read_b128 v[156:159], v165 offset:2048
	ds_read_b128 v[170:173], v165 offset:3072
	s_add_u32 s34, s76, 0xfffc0080
	s_addc_u32 s35, s77, -1
	s_cmp_eq_u32 s15, 12
	s_cselect_b32 s81, s47, s35
	s_cselect_b32 s80, s55, s34
	s_cselect_b32 s79, s31, s14
	s_cselect_b32 s78, s57, vcc_lo
	v_lshl_add_u64 v[160:161], s[76:77], 0, v[140:141]
	s_add_i32 m0, s85, 0xc000
	ds_read_b128 v[174:177], v166
	ds_read_b128 v[178:181], v166 offset:1024
	ds_read_b128 v[182:185], v166 offset:2048
	ds_read_b128 v[186:189], v166 offset:3072
	ds_read_b128 v[190:193], v166 offset:4096
	ds_read_b128 v[194:197], v166 offset:5120
	ds_read_b128 v[198:201], v166 offset:6144
	ds_read_b128 v[202:205], v166 offset:7168
	global_load_lds_dwordx4 v[160:161], off
	v_lshl_add_u64 v[160:161], s[76:77], 0, v[142:143]
	s_add_i32 m0, s85, 0xe000
	s_nop 0
	global_load_lds_dwordx4 v[160:161], off
	s_waitcnt lgkmcnt(8)
	s_barrier
	s_waitcnt lgkmcnt(0)
	s_waitcnt lgkmcnt(0)
	v_mfma_f32_16x16x32_f16 v[124:127], v[148:151], v[174:177], v[124:127]
	v_mfma_f32_16x16x32_f16 v[120:123], v[156:159], v[174:177], v[120:123]
	v_mfma_f32_16x16x32_f16 v[116:119], v[148:151], v[182:185], v[116:119]
	v_mfma_f32_16x16x32_f16 v[112:115], v[156:159], v[182:185], v[112:115]
	v_mfma_f32_16x16x32_f16 v[108:111], v[148:151], v[190:193], v[108:111]
	v_mfma_f32_16x16x32_f16 v[104:107], v[156:159], v[190:193], v[104:107]
	v_mfma_f32_16x16x32_f16 v[100:103], v[148:151], v[198:201], v[100:103]
	v_mfma_f32_16x16x32_f16 v[96:99], v[156:159], v[198:201], v[96:99]
	v_mfma_f32_16x16x32_f16 v[124:127], v[152:155], v[178:181], v[124:127]
	v_mfma_f32_16x16x32_f16 v[120:123], v[170:173], v[178:181], v[120:123]
	v_mfma_f32_16x16x32_f16 v[116:119], v[152:155], v[186:189], v[116:119]
	v_mfma_f32_16x16x32_f16 v[112:115], v[170:173], v[186:189], v[112:115]
	v_mfma_f32_16x16x32_f16 v[108:111], v[152:155], v[194:197], v[108:111]
	v_mfma_f32_16x16x32_f16 v[104:107], v[170:173], v[194:197], v[104:107]
	v_mfma_f32_16x16x32_f16 v[100:103], v[152:155], v[202:205], v[100:103]
	v_mfma_f32_16x16x32_f16 v[96:99], v[170:173], v[202:205], v[96:99]
	s_barrier
	s_add_i32 s34, s95, s84
	v_lshl_add_u64 v[160:161], s[78:79], 0, v[132:133]
	s_mov_b32 m0, s34
	ds_read_b128 v[206:209], v167
	ds_read_b128 v[210:213], v167 offset:1024
	ds_read_b128 v[214:217], v167 offset:2048
	ds_read_b128 v[218:221], v167 offset:3072
	global_load_lds_dwordx4 v[160:161], off
	v_lshl_add_u64 v[222:223], s[78:79], 0, v[136:137]
	s_add_i32 m0, s34, 0x2000
	s_nop 0
	global_load_lds_dwordx4 v[222:223], off
	s_barrier
	s_waitcnt lgkmcnt(0)
	s_waitcnt lgkmcnt(0)
	s_cmp_eq_u32 s54, 20
	s_cbranch_scc1 .Lg3_skip0
	v_mfma_f32_16x16x32_f16 v[60:63], v[206:209], v[174:177], v[60:63]
	v_mfma_f32_16x16x32_f16 v[56:59], v[214:217], v[174:177], v[56:59]
	v_mfma_f32_16x16x32_f16 v[52:55], v[206:209], v[182:185], v[52:55]
	v_mfma_f32_16x16x32_f16 v[48:51], v[214:217], v[182:185], v[48:51]
	v_mfma_f32_16x16x32_f16 v[44:47], v[206:209], v[190:193], v[44:47]
	v_mfma_f32_16x16x32_f16 v[40:43], v[214:217], v[190:193], v[40:43]
	v_mfma_f32_16x16x32_f16 v[36:39], v[206:209], v[198:201], v[36:39]
	v_mfma_f32_16x16x32_f16 v[32:35], v[214:217], v[198:201], v[32:35]
	v_mfma_f32_16x16x32_f16 v[60:63], v[210:213], v[178:181], v[60:63]
	v_mfma_f32_16x16x32_f16 v[56:59], v[218:221], v[178:181], v[56:59]
	v_mfma_f32_16x16x32_f16 v[52:55], v[210:213], v[186:189], v[52:55]
	v_mfma_f32_16x16x32_f16 v[48:51], v[218:221], v[186:189], v[48:51]
	v_mfma_f32_16x16x32_f16 v[44:47], v[210:213], v[194:197], v[44:47]
	v_mfma_f32_16x16x32_f16 v[40:43], v[218:221], v[194:197], v[40:43]
	v_mfma_f32_16x16x32_f16 v[36:39], v[210:213], v[202:205], v[36:39]
	v_mfma_f32_16x16x32_f16 v[32:35], v[218:221], v[202:205], v[32:35]
.Lg3_skip0:
	s_mov_b32 m0, s85
	v_lshl_add_u64 v[224:225], s[80:81], 0, v[128:129]
	s_barrier
	ds_read_b128 v[174:177], v166 offset:16384
	ds_read_b128 v[178:181], v166 offset:17408
	ds_read_b128 v[182:185], v166 offset:18432
	ds_read_b128 v[186:189], v166 offset:19456
	ds_read_b128 v[190:193], v166 offset:20480
	ds_read_b128 v[194:197], v166 offset:21504
	ds_read_b128 v[198:201], v166 offset:22528
	ds_read_b128 v[202:205], v166 offset:23552
	global_load_lds_dwordx4 v[224:225], off
	v_lshl_add_u64 v[226:227], s[80:81], 0, v[134:135]
	s_mov_b32 m0, s86
	s_nop 0
	global_load_lds_dwordx4 v[226:227], off
	s_barrier
	s_waitcnt lgkmcnt(0)
	s_waitcnt lgkmcnt(0)
	v_mfma_f32_16x16x32_f16 v[92:95], v[148:151], v[174:177], v[92:95]
	v_mfma_f32_16x16x32_f16 v[88:91], v[156:159], v[174:177], v[88:91]
	v_mfma_f32_16x16x32_f16 v[84:87], v[148:151], v[182:185], v[84:87]
	v_mfma_f32_16x16x32_f16 v[80:83], v[156:159], v[182:185], v[80:83]
	v_mfma_f32_16x16x32_f16 v[76:79], v[148:151], v[190:193], v[76:79]
	v_mfma_f32_16x16x32_f16 v[72:75], v[156:159], v[190:193], v[72:75]
	v_mfma_f32_16x16x32_f16 v[68:71], v[148:151], v[198:201], v[68:71]
	v_mfma_f32_16x16x32_f16 v[64:67], v[156:159], v[198:201], v[64:67]
	v_mfma_f32_16x16x32_f16 v[92:95], v[152:155], v[178:181], v[92:95]
	v_mfma_f32_16x16x32_f16 v[88:91], v[170:173], v[178:181], v[88:91]
	v_mfma_f32_16x16x32_f16 v[84:87], v[152:155], v[186:189], v[84:87]
	v_mfma_f32_16x16x32_f16 v[80:83], v[170:173], v[186:189], v[80:83]
	v_mfma_f32_16x16x32_f16 v[76:79], v[152:155], v[194:197], v[76:79]
	v_mfma_f32_16x16x32_f16 v[72:75], v[170:173], v[194:197], v[72:75]
	v_mfma_f32_16x16x32_f16 v[68:71], v[152:155], v[202:205], v[68:71]
	v_mfma_f32_16x16x32_f16 v[64:67], v[170:173], v[202:205], v[64:67]
	s_barrier
	s_add_u32 s34, s78, 0x40000
	s_addc_u32 s35, s79, 0
	s_add_i32 vcc_hi, s96, s84
	v_lshl_add_u64 v[148:149], s[34:35], 0, v[132:133]
	s_mov_b32 m0, vcc_hi
	s_nop 0
	global_load_lds_dwordx4 v[148:149], off
	v_lshl_add_u64 v[148:149], s[34:35], 0, v[136:137]
	s_add_i32 m0, vcc_hi, 0x2000
	s_nop 0
	global_load_lds_dwordx4 v[148:149], off
	s_waitcnt vmcnt(6)
	s_barrier
	s_cmp_eq_u32 s54, 20
	s_cbranch_scc1 .Lg3_skip1
	v_mfma_f32_16x16x32_f16 v[28:31], v[206:209], v[174:177], v[28:31]
	v_mfma_f32_16x16x32_f16 v[24:27], v[214:217], v[174:177], v[24:27]
	v_mfma_f32_16x16x32_f16 v[20:23], v[206:209], v[182:185], v[20:23]
	v_mfma_f32_16x16x32_f16 v[16:19], v[214:217], v[182:185], v[16:19]
	v_mfma_f32_16x16x32_f16 v[12:15], v[206:209], v[190:193], v[12:15]
	v_mfma_f32_16x16x32_f16 v[8:11], v[214:217], v[190:193], v[8:11]
	v_mfma_f32_16x16x32_f16 v[4:7], v[206:209], v[198:201], v[4:7]
	v_mfma_f32_16x16x32_f16 v[0:3], v[214:217], v[198:201], v[0:3]
	v_mfma_f32_16x16x32_f16 v[28:31], v[210:213], v[178:181], v[28:31]
	v_mfma_f32_16x16x32_f16 v[24:27], v[218:221], v[178:181], v[24:27]
	v_mfma_f32_16x16x32_f16 v[20:23], v[210:213], v[186:189], v[20:23]
	v_mfma_f32_16x16x32_f16 v[16:19], v[218:221], v[186:189], v[16:19]
	v_mfma_f32_16x16x32_f16 v[12:15], v[210:213], v[194:197], v[12:15]
	v_mfma_f32_16x16x32_f16 v[8:11], v[218:221], v[194:197], v[8:11]
	v_mfma_f32_16x16x32_f16 v[4:7], v[210:213], v[202:205], v[4:7]
	v_mfma_f32_16x16x32_f16 v[0:3], v[218:221], v[202:205], v[0:3]
; #define PG8_STAGE(bufoff, gbase, voff) do { _Pragma("unroll") for (int _i = 0; _i < 2; ++_i) \
;         __builtin_amdgcn_global_load_lds((const unsigned*)((const char*)(gbase) + (voff)[_i]), (LAS unsigned*)(lds + (bufoff) + ldsw + _i * 8192), 16, 0, 0); } while (0)
; #define PG8_LDA(dst, b, h) do { _Pragma("unroll") for (int m = 0; m < 4; ++m) _Pragma("unroll") for (int k = 0; k < 2; ++k) dst[m][k] = *(const LAS h16x8*)(lds + PG8_SA(b, h) + aoff + m * 2048 + k * 1024); } while (0)
; #define PG8_LDB(dst, b, h) do { _Pragma("unroll") for (int n = 0; n < 2; ++n) _Pragma("unroll") for (int k = 0; k < 2; ++k) dst[n][k] = *(const LAS h16x8*)(lds + PG8_SB(b, h) + boff + n * 2048 + k * 1024); } while (0)
; #define PG8_MMA(ai, bj, At, Bt) do { __builtin_amdgcn_s_setprio(1); _Pragma("unroll") for (int m = 0; m < 4; ++m) _Pragma("unroll") for (int n = 0; n < 2; ++n) _Pragma("unroll") for (int k = 0; k < 2; ++k) \
;         acc[ai][bj][m][n] = __builtin_amdgcn_mfma_f32_16x16x32_f16(Bt[n][k], At[m][k], acc[ai][bj][m][n], 0, 0, 0); __builtin_amdgcn_s_setprio(0); } while (0)
; #define PG8_WAIT_L(n) asm volatile("s_waitcnt lgkmcnt(" #n ")" ::: "memory")
; #define PG8_BAR __builtin_amdgcn_s_barrier()
; #define PG8_SCHED __builtin_amdgcn_sched_barrier(0)
; template <class Epi>
; __device__ __forceinline__ void gemm_phase(LAS unsigned char* lds, const Gemm g, const StaticOrder& S, const Epi& E) {
;     ...
;             PG8_LDB(B0, 1, 0); PG8_SCHED; PG8_LDA(At, 1, 0); PG8_STAGE(PG8_SA(0, 1), a2 + hstep, voffA);
;             PG8_WAIT_L(8); PG8_BAR; PG8_WAIT_L(0); PG8_MMA(0, 0, At, B0); PG8_BAR; PG8_SCHED;
;             PG8_LDB(B1, 1, 1); PG8_STAGE(PG8_SB(1, 0), b3, voffB);
;             PG8_BAR; PG8_WAIT_L(0); PG8_MMA(0, 1, At, B1); PG8_BAR;
.Lg3_skip1:
	s_add_i32 vcc_hi, 0, 0x18000
	v_add_u32_e32 v138, vcc_hi, v163
	s_barrier
	ds_read_b128 v[148:151], v138
	ds_read_b128 v[152:155], v138 offset:1024
	ds_read_b128 v[156:159], v138 offset:2048
	ds_read_b128 v[170:173], v138 offset:3072
	s_add_u32 s34, s80, 0x40000
	s_addc_u32 s35, s81, 0
	s_mov_b32 m0, s87
	v_lshl_add_u64 v[206:207], s[34:35], 0, v[128:129]
	ds_read_b128 v[174:177], v166 offset:32768
	ds_read_b128 v[178:181], v166 offset:33792
	ds_read_b128 v[182:185], v166 offset:34816
	ds_read_b128 v[186:189], v166 offset:35840
	ds_read_b128 v[190:193], v166 offset:36864
	ds_read_b128 v[194:197], v166 offset:37888
	ds_read_b128 v[198:201], v166 offset:38912
	ds_read_b128 v[202:205], v166 offset:39936
	global_load_lds_dwordx4 v[206:207], off
	v_lshl_add_u64 v[206:207], s[34:35], 0, v[134:135]
	s_mov_b32 m0, s88
	s_nop 0
	global_load_lds_dwordx4 v[206:207], off
	s_waitcnt lgkmcnt(8)
	s_barrier
	s_waitcnt lgkmcnt(0)
	s_waitcnt lgkmcnt(0)
	v_mfma_f32_16x16x32_f16 v[124:127], v[148:151], v[174:177], v[124:127]
	v_mfma_f32_16x16x32_f16 v[120:123], v[156:159], v[174:177], v[120:123]
	v_mfma_f32_16x16x32_f16 v[116:119], v[148:151], v[182:185], v[116:119]
	v_mfma_f32_16x16x32_f16 v[112:115], v[156:159], v[182:185], v[112:115]
	v_mfma_f32_16x16x32_f16 v[108:111], v[148:151], v[190:193], v[108:111]
	v_mfma_f32_16x16x32_f16 v[104:107], v[156:159], v[190:193], v[104:107]
	v_mfma_f32_16x16x32_f16 v[100:103], v[148:151], v[198:201], v[100:103]
	v_mfma_f32_16x16x32_f16 v[96:99], v[156:159], v[198:201], v[96:99]
	v_mfma_f32_16x16x32_f16 v[124:127], v[152:155], v[178:181], v[124:127]
	v_mfma_f32_16x16x32_f16 v[120:123], v[170:173], v[178:181], v[120:123]
	v_mfma_f32_16x16x32_f16 v[116:119], v[152:155], v[186:189], v[116:119]
	v_mfma_f32_16x16x32_f16 v[112:115], v[170:173], v[186:189], v[112:115]
	v_mfma_f32_16x16x32_f16 v[108:111], v[152:155], v[194:197], v[108:111]
	v_mfma_f32_16x16x32_f16 v[104:107], v[170:173], v[194:197], v[104:107]
	v_mfma_f32_16x16x32_f16 v[100:103], v[152:155], v[202:205], v[100:103]
	v_mfma_f32_16x16x32_f16 v[96:99], v[170:173], v[202:205], v[96:99]
	s_barrier
	s_add_i32 s80, 0, 0x1c000
	s_add_i32 s34, vcc_hi, s84
	v_add_u32_e32 v138, s80, v163
	v_lshl_add_u64 v[160:161], v[160:161], 0, s[12:13]
	s_mov_b32 m0, s34
	ds_read_b128 v[206:209], v138
	ds_read_b128 v[210:213], v138 offset:1024
	ds_read_b128 v[214:217], v138 offset:2048
	ds_read_b128 v[218:221], v138 offset:3072
	global_load_lds_dwordx4 v[160:161], off
	v_lshl_add_u64 v[160:161], v[222:223], 0, s[12:13]
	s_add_i32 m0, s34, 0x2000
	s_nop 0
	global_load_lds_dwordx4 v[160:161], off
	s_barrier
	s_waitcnt lgkmcnt(0)
	s_waitcnt lgkmcnt(0)
	s_cmp_eq_u32 s54, 20
	s_cbranch_scc1 .Lg3_skip2
	v_mfma_f32_16x16x32_f16 v[60:63], v[206:209], v[174:177], v[60:63]
	v_mfma_f32_16x16x32_f16 v[56:59], v[214:217], v[174:177], v[56:59]
	v_mfma_f32_16x16x32_f16 v[52:55], v[206:209], v[182:185], v[52:55]
	v_mfma_f32_16x16x32_f16 v[48:51], v[214:217], v[182:185], v[48:51]
	v_mfma_f32_16x16x32_f16 v[44:47], v[206:209], v[190:193], v[44:47]
	v_mfma_f32_16x16x32_f16 v[40:43], v[214:217], v[190:193], v[40:43]
	v_mfma_f32_16x16x32_f16 v[36:39], v[206:209], v[198:201], v[36:39]
	v_mfma_f32_16x16x32_f16 v[32:35], v[214:217], v[198:201], v[32:35]
	v_mfma_f32_16x16x32_f16 v[60:63], v[210:213], v[178:181], v[60:63]
	v_mfma_f32_16x16x32_f16 v[56:59], v[218:221], v[178:181], v[56:59]
	v_mfma_f32_16x16x32_f16 v[52:55], v[210:213], v[186:189], v[52:55]
	v_mfma_f32_16x16x32_f16 v[48:51], v[218:221], v[186:189], v[48:51]
	v_mfma_f32_16x16x32_f16 v[44:47], v[210:213], v[194:197], v[44:47]
	v_mfma_f32_16x16x32_f16 v[40:43], v[218:221], v[194:197], v[40:43]
	v_mfma_f32_16x16x32_f16 v[36:39], v[210:213], v[202:205], v[36:39]
	v_mfma_f32_16x16x32_f16 v[32:35], v[218:221], v[202:205], v[32:35]
; #define PG8_STAGE(bufoff, gbase, voff) do { _Pragma("unroll") for (int _i = 0; _i < 2; ++_i) \
;         __builtin_amdgcn_global_load_lds((const unsigned*)((const char*)(gbase) + (voff)[_i]), (LAS unsigned*)(lds + (bufoff) + ldsw + _i * 8192), 16, 0, 0); } while (0)
; #define PG8_LDA(dst, b, h) do { _Pragma("unroll") for (int m = 0; m < 4; ++m) _Pragma("unroll") for (int k = 0; k < 2; ++k) dst[m][k] = *(const LAS h16x8*)(lds + PG8_SA(b, h) + aoff + m * 2048 + k * 1024); } while (0)
; #define PG8_MMA(ai, bj, At, Bt) do { __builtin_amdgcn_s_setprio(1); _Pragma("unroll") for (int m = 0; m < 4; ++m) _Pragma("unroll") for (int n = 0; n < 2; ++n) _Pragma("unroll") for (int k = 0; k < 2; ++k) \
;         acc[ai][bj][m][n] = __builtin_amdgcn_mfma_f32_16x16x32_f16(Bt[n][k], At[m][k], acc[ai][bj][m][n], 0, 0, 0); __builtin_amdgcn_s_setprio(0); } while (0)
; #define PG8_WAIT_V(n) asm volatile("s_waitcnt vmcnt(" #n ")" ::: "memory")
; #define PG8_WAIT_L(n) asm volatile("s_waitcnt lgkmcnt(" #n ")" ::: "memory")
; #define PG8_BAR __builtin_amdgcn_s_barrier()
; #define PG8_SCHED __builtin_amdgcn_sched_barrier(0)
; template <class Epi>
; __device__ __forceinline__ void gemm_phase(LAS unsigned char* lds, const Gemm g, const StaticOrder& S, const Epi& E) {
;     ...
;             PG8_LDA(At, 1, 1); PG8_STAGE(PG8_SA(1, 0), a3, voffA);
;             PG8_BAR; PG8_WAIT_L(0); PG8_MMA(1, 0, At, B0); PG8_BAR; PG8_SCHED;
;             PG8_STAGE(PG8_SB(1, 1), b3 + hstep, voffB);
;             PG8_WAIT_V(6); PG8_BAR; PG8_MMA(1, 1, At, B1); PG8_BAR;
;     __device__ __forceinline__ void operator()(const f32x4 (&acc)[2][2][4][2], const pg8::Unit& u, int wr, int wc, int fr, int fq) const {
;         const int row0 = u.pm * 256 + wr * 64 + fr, col0 = u.pn * 256 + wc * 32 + 8 * fq;
; #pragma unroll
;         for (int bj = 0; bj < 2; ++bj) { const int c = col0 + bj * 128;
;             h16* base; size_t ld;
;             if (c < 3200) { base = PC + c; ld = 3200; }
;             else if (c < 4224) { base = ZCD + (c - 3200); ld = 1536; }
;             else if (c < 4736) {
.Lg3_skip2:
	s_mov_b32 m0, s92
	v_lshl_add_u64 v[160:161], v[224:225], 0, s[12:13]
	s_barrier
	ds_read_b128 v[174:177], v166 offset:49152
	ds_read_b128 v[178:181], v166 offset:50176
	ds_read_b128 v[182:185], v166 offset:51200
	ds_read_b128 v[186:189], v166 offset:52224
	ds_read_b128 v[190:193], v166 offset:53248
	ds_read_b128 v[194:197], v166 offset:54272
	ds_read_b128 v[198:201], v166 offset:55296
	ds_read_b128 v[202:205], v166 offset:56320
	global_load_lds_dwordx4 v[160:161], off
	v_lshl_add_u64 v[160:161], v[226:227], 0, s[12:13]
	s_mov_b32 m0, s93
	s_nop 0
	global_load_lds_dwordx4 v[160:161], off
	s_barrier
	s_waitcnt lgkmcnt(0)
	s_waitcnt lgkmcnt(0)
	v_mfma_f32_16x16x32_f16 v[92:95], v[148:151], v[174:177], v[92:95]
	v_mfma_f32_16x16x32_f16 v[88:91], v[156:159], v[174:177], v[88:91]
	v_mfma_f32_16x16x32_f16 v[84:87], v[148:151], v[182:185], v[84:87]
	v_mfma_f32_16x16x32_f16 v[80:83], v[156:159], v[182:185], v[80:83]
	v_mfma_f32_16x16x32_f16 v[76:79], v[148:151], v[190:193], v[76:79]
	v_mfma_f32_16x16x32_f16 v[72:75], v[156:159], v[190:193], v[72:75]
	v_mfma_f32_16x16x32_f16 v[68:71], v[148:151], v[198:201], v[68:71]
	v_mfma_f32_16x16x32_f16 v[64:67], v[156:159], v[198:201], v[64:67]
	v_mfma_f32_16x16x32_f16 v[92:95], v[152:155], v[178:181], v[92:95]
	v_mfma_f32_16x16x32_f16 v[88:91], v[170:173], v[178:181], v[88:91]
	v_mfma_f32_16x16x32_f16 v[84:87], v[152:155], v[186:189], v[84:87]
	v_mfma_f32_16x16x32_f16 v[80:83], v[170:173], v[186:189], v[80:83]
	v_mfma_f32_16x16x32_f16 v[76:79], v[152:155], v[194:197], v[76:79]
	v_mfma_f32_16x16x32_f16 v[72:75], v[170:173], v[194:197], v[72:75]
	v_mfma_f32_16x16x32_f16 v[68:71], v[152:155], v[202:205], v[68:71]
	v_mfma_f32_16x16x32_f16 v[64:67], v[170:173], v[202:205], v[64:67]
	s_barrier
	s_add_u32 s34, s78, 0x40080
	s_addc_u32 s35, s79, 0
	s_add_i32 s78, s80, s84
	v_lshl_add_u64 v[148:149], s[34:35], 0, v[132:133]
	s_mov_b32 m0, s78
	s_nop 0
	global_load_lds_dwordx4 v[148:149], off
	v_lshl_add_u64 v[148:149], s[34:35], 0, v[136:137]
	s_add_i32 m0, s78, 0x2000
	s_nop 0
	global_load_lds_dwordx4 v[148:149], off
	s_waitcnt vmcnt(6)
	s_barrier
	s_cmp_eq_u32 s54, 20
	s_cbranch_scc1 .Lg3_skip3
	v_mfma_f32_16x16x32_f16 v[28:31], v[206:209], v[174:177], v[28:31]
	v_mfma_f32_16x16x32_f16 v[24:27], v[214:217], v[174:177], v[24:27]
	v_mfma_f32_16x16x32_f16 v[20:23], v[206:209], v[182:185], v[20:23]
	v_mfma_f32_16x16x32_f16 v[16:19], v[214:217], v[182:185], v[16:19]
	v_mfma_f32_16x16x32_f16 v[12:15], v[206:209], v[190:193], v[12:15]
	v_mfma_f32_16x16x32_f16 v[8:11], v[214:217], v[190:193], v[8:11]
	v_mfma_f32_16x16x32_f16 v[4:7], v[206:209], v[198:201], v[4:7]
	v_mfma_f32_16x16x32_f16 v[0:3], v[214:217], v[198:201], v[0:3]
	v_mfma_f32_16x16x32_f16 v[28:31], v[210:213], v[178:181], v[28:31]
	v_mfma_f32_16x16x32_f16 v[24:27], v[218:221], v[178:181], v[24:27]
	v_mfma_f32_16x16x32_f16 v[20:23], v[210:213], v[186:189], v[20:23]
	v_mfma_f32_16x16x32_f16 v[16:19], v[218:221], v[186:189], v[16:19]
	v_mfma_f32_16x16x32_f16 v[12:15], v[210:213], v[194:197], v[12:15]
	v_mfma_f32_16x16x32_f16 v[8:11], v[218:221], v[194:197], v[8:11]
	v_mfma_f32_16x16x32_f16 v[4:7], v[210:213], v[202:205], v[4:7]
	v_mfma_f32_16x16x32_f16 v[0:3], v[218:221], v[202:205], v[0:3]
.Lg3_skip3:
	s_add_i32 s15, s15, 2
	s_add_u32 s76, s76, 0x100
	s_addc_u32 s77, s77, 0
	s_add_u32 vcc_lo, vcc_lo, 0x100
	s_addc_u32 s14, s14, 0
	s_cmp_gt_u32 s15, 13
	s_barrier
	s_cbranch_scc0 .LBB0_485
	s_lshl_b32 s14, s54, 8
	v_or_b32_e32 v154, s14, v164
	v_lshl_add_u32 v148, s56, 8, v162
	v_cmp_lt_i32_e32 vcc, s97, v154
	s_mov_b64 s[56:57], 0
	s_and_saveexec_b64 s[34:35], vcc
	s_xor_b64 s[54:55], exec, s[34:35]
	s_cbranch_execz .LBB0_498
	s_cmpk_gt_u32 s14, 0x107f
	s_cbranch_scc0 .LBB0_491
	s_cmpk_gt_u32 s14, 0x127f
	s_cbranch_scc0 .LBB0_492
	s_mov_b64 s[76:77], 0
	s_cmpk_lt_u32 s14, 0x1480
	s_cbranch_scc0 .LBB0_493
	v_mov_b32_e32 v155, v139
	v_lshl_add_u64 v[150:151], v[154:155], 1, s[8:9]
	v_lshl_add_u64 v[158:159], v[150:151], 0, s[18:19]
	s_mov_b64 s[56:57], -1
	s_branch .LBB0_493
